# grid barrier: L1 invalidate issued at arrival (overlaps the poll) instead of after release; all loads of the CU are drained before arrival so no L1 fill can happen in between
# speedup vs baseline: 1.0105x; 1.0089x over previous
.LBB0_188:
	s_or_b64 exec, exec, s[10:11]
	v_cvt_f32_u32_e32 v7, v4
	s_waitcnt vmcnt(0)
	v_readfirstlane_b32 s10, v5
	v_sub_u32_e32 v5, 0, v4
	v_rcp_iflag_f32_e32 v7, v7
	v_add_u32_e32 v8, s10, v1
	v_mul_f32_e32 v7, 0x4f7ffffe, v7
	v_cvt_u32_f32_e32 v7, v7
	v_mul_lo_u32 v1, v5, v7
	v_mul_hi_u32 v1, v7, v1
	v_add_u32_e32 v1, v7, v1
	v_mul_hi_u32 v1, v8, v1
	v_mul_lo_u32 v5, v1, v4
	v_sub_u32_e32 v5, v8, v5
	v_add_u32_e32 v7, 1, v1
	v_cmp_ge_u32_e32 vcc, v5, v4
	s_nop 1
	v_cndmask_b32_e32 v1, v1, v7, vcc
	v_sub_u32_e32 v7, v5, v4
	v_cndmask_b32_e32 v5, v5, v7, vcc
	v_add_u32_e32 v7, 1, v1
	v_cmp_ge_u32_e32 vcc, v5, v4
	v_add_u32_e32 v5, 1, v8
	s_nop 0
	v_cndmask_b32_e32 v1, v1, v7, vcc
	v_mul_lo_u32 v7, v4, v1
	v_add_u32_e32 v4, v7, v4
	v_cmp_ne_u32_e32 vcc, v5, v4
	buffer_inv sc1
	v_add_u32_e32 v8, 1, v1
	v_readlane_b32 s12, v252, 39
	v_readlane_b32 s13, v252, 40
	s_waitcnt lgkmcnt(0)
	v_mul_lo_u32 v7, v8, v2
	v_mov_b32_e32 v5, 1
	s_mov_b32 s25, 0
	s_nop 4
	s_cbranch_vccnz .Lxb_poll_1
	buffer_wbl2 sc1
	s_waitcnt vmcnt(0)
	global_atomic_add v3, v5, s[12:13]

.Lxb_done_1:
	s_waitcnt vmcnt(0)
.LBB0_222:
	s_or_b64 exec, exec, s[6:7]
	s_waitcnt lgkmcnt(0)
	s_barrier

.LBB0_296:
	s_or_b64 exec, exec, s[12:13]
	v_cvt_f32_u32_e32 v7, v4
	s_waitcnt vmcnt(0)
	v_readfirstlane_b32 s12, v5
	v_sub_u32_e32 v5, 0, v4
	v_rcp_iflag_f32_e32 v7, v7
	v_add_u32_e32 v8, s12, v1
	v_mul_f32_e32 v7, 0x4f7ffffe, v7
	v_cvt_u32_f32_e32 v7, v7
	v_mul_lo_u32 v1, v5, v7
	v_mul_hi_u32 v1, v7, v1
	v_add_u32_e32 v1, v7, v1
	v_mul_hi_u32 v1, v8, v1
	v_mul_lo_u32 v5, v1, v4
	v_sub_u32_e32 v5, v8, v5
	v_add_u32_e32 v7, 1, v1
	v_cmp_ge_u32_e32 vcc, v5, v4
	s_nop 1
	v_cndmask_b32_e32 v1, v1, v7, vcc
	v_sub_u32_e32 v7, v5, v4
	v_cndmask_b32_e32 v5, v5, v7, vcc
	v_add_u32_e32 v7, 1, v1
	v_cmp_ge_u32_e32 vcc, v5, v4
	v_add_u32_e32 v5, 1, v8
	s_nop 0
	v_cndmask_b32_e32 v1, v1, v7, vcc
	v_mul_lo_u32 v7, v4, v1
	v_add_u32_e32 v4, v7, v4
	v_cmp_ne_u32_e32 vcc, v5, v4
	buffer_inv sc1
	v_add_u32_e32 v8, 1, v1
	v_readlane_b32 s14, v252, 39
	v_readlane_b32 s15, v252, 40
	s_waitcnt lgkmcnt(0)
	v_mul_lo_u32 v7, v8, v2
	v_mov_b32_e32 v5, 1
	s_mov_b32 s26, 0
	s_nop 4
	s_cbranch_vccnz .Lxb_poll_2
	buffer_wbl2 sc1
	s_waitcnt vmcnt(0)
	global_atomic_add v3, v5, s[14:15]

.Lxb_done_2:
	s_waitcnt vmcnt(0)
	v_readlane_b32 s26, v254, 40
	v_readlane_b32 s27, v254, 41
	s_mov_b32 s24, 0x32900000

.Lxb_done_3:
	s_waitcnt vmcnt(0)
.LBB0_439:
	s_or_b64 exec, exec, s[6:7]
	s_waitcnt lgkmcnt(0)
	s_barrier

.Lxb_done_4:
	s_waitcnt vmcnt(0)
.LBB0_522:
	s_or_b64 exec, exec, s[6:7]
	s_waitcnt lgkmcnt(0)
	s_barrier

.Lxb_done_5:
	s_waitcnt vmcnt(0)
.LBB0_684:
	s_or_b64 exec, exec, s[8:9]
	s_waitcnt lgkmcnt(0)
	s_barrier

.LBB0_940:
	s_or_b64 exec, exec, s[8:9]
	v_cvt_f32_u32_e32 v7, v4
	s_waitcnt vmcnt(0)
	v_readfirstlane_b32 s8, v5
	v_sub_u32_e32 v5, 0, v4
	v_rcp_iflag_f32_e32 v7, v7
	v_add_u32_e32 v8, s8, v1
	v_mul_f32_e32 v7, 0x4f7ffffe, v7
	v_cvt_u32_f32_e32 v7, v7
	v_mul_lo_u32 v1, v5, v7
	v_mul_hi_u32 v1, v7, v1
	v_add_u32_e32 v1, v7, v1
	v_mul_hi_u32 v1, v8, v1
	v_mul_lo_u32 v5, v1, v4
	v_sub_u32_e32 v5, v8, v5
	v_add_u32_e32 v7, 1, v1
	v_cmp_ge_u32_e32 vcc, v5, v4
	s_nop 1
	v_cndmask_b32_e32 v1, v1, v7, vcc
	v_sub_u32_e32 v7, v5, v4
	v_cndmask_b32_e32 v5, v5, v7, vcc
	v_add_u32_e32 v7, 1, v1
	v_cmp_ge_u32_e32 vcc, v5, v4
	v_add_u32_e32 v5, 1, v8
	s_nop 0
	v_cndmask_b32_e32 v1, v1, v7, vcc
	v_mul_lo_u32 v7, v4, v1
	v_add_u32_e32 v4, v7, v4
	v_cmp_ne_u32_e32 vcc, v5, v4
	buffer_inv sc1
	v_add_u32_e32 v8, 1, v1
	v_readlane_b32 s10, v252, 39
	v_readlane_b32 s11, v252, 40
	s_waitcnt lgkmcnt(0)
	v_mul_lo_u32 v7, v8, v2
	v_mov_b32_e32 v5, 1
	s_mov_b32 s22, 0
	s_nop 4
	s_cbranch_vccnz .Lxb_poll_6
	buffer_wbl2 sc1
	s_waitcnt vmcnt(0)
	global_atomic_add v3, v5, s[10:11]

.Lxb_done_6:
	s_waitcnt vmcnt(0)
.LBB0_974:
	s_or_b64 exec, exec, s[6:7]
	s_mov_b64 s[10:11], -1
	s_waitcnt lgkmcnt(0)
	s_barrier

.Lxb_done_7:
	s_waitcnt vmcnt(0)
.LBB0_1122:
	s_or_b64 exec, exec, s[8:9]
	s_waitcnt lgkmcnt(0)
	s_barrier

.Lxb_done_8:
	s_waitcnt vmcnt(0)
.LBB0_1219:
	s_or_b64 exec, exec, s[8:9]
	s_waitcnt lgkmcnt(0)
	s_barrier

.Lxb_done_9:
	s_waitcnt vmcnt(0)
.LBB0_1456:
	s_or_b64 exec, exec, s[6:7]
	s_mov_b64 s[10:11], -1
	s_waitcnt lgkmcnt(0)
	s_barrier

.LBB0_1508:
	s_or_b64 exec, exec, s[10:11]
	v_cvt_f32_u32_e32 v7, v4
	s_waitcnt vmcnt(0)
	v_readfirstlane_b32 s10, v5
	v_sub_u32_e32 v5, 0, v4
	v_rcp_iflag_f32_e32 v7, v7
	v_add_u32_e32 v8, s10, v1
	v_mul_f32_e32 v7, 0x4f7ffffe, v7
	v_cvt_u32_f32_e32 v7, v7
	v_mul_lo_u32 v1, v5, v7
	v_mul_hi_u32 v1, v7, v1
	v_add_u32_e32 v1, v7, v1
	v_mul_hi_u32 v1, v8, v1
	v_mul_lo_u32 v5, v1, v4
	v_sub_u32_e32 v5, v8, v5
	v_add_u32_e32 v7, 1, v1
	v_cmp_ge_u32_e32 vcc, v5, v4
	s_nop 1
	v_cndmask_b32_e32 v1, v1, v7, vcc
	v_sub_u32_e32 v7, v5, v4
	v_cndmask_b32_e32 v5, v5, v7, vcc
	v_add_u32_e32 v7, 1, v1
	v_cmp_ge_u32_e32 vcc, v5, v4
	v_add_u32_e32 v5, 1, v8
	s_nop 0
	v_cndmask_b32_e32 v1, v1, v7, vcc
	v_mul_lo_u32 v7, v4, v1
	v_add_u32_e32 v4, v7, v4
	v_cmp_ne_u32_e32 vcc, v5, v4
	buffer_inv sc1
	v_add_u32_e32 v8, 1, v1
	v_readlane_b32 s12, v252, 39
	v_readlane_b32 s13, v252, 40
	s_waitcnt lgkmcnt(0)
	v_mul_lo_u32 v7, v8, v2
	v_mov_b32_e32 v5, 1
	s_mov_b32 s24, 0
	s_nop 4
	s_cbranch_vccnz .Lxb_poll_10
	buffer_wbl2 sc1
	s_waitcnt vmcnt(0)
	global_atomic_add v3, v5, s[12:13]

.Lxb_done_10:
	s_waitcnt vmcnt(0)
	s_mov_b32 s24, 0x32900000
	s_mov_b64 s[12:13], 0
	s_getpc_b64 s[98:99]
